# compression-block gather: positional-embedding base pointers loaded once instead of per element, its loads issued with the row load
# baseline (speedup 1.0000x reference)
.LBB0_1160:
	s_load_dwordx2 s[2:3], s[0:1], 0x310
	s_waitcnt lgkmcnt(0)
	s_cmp_lt_i32 s2, 13
	s_cselect_b64 s[2:3], -1, 0
	s_and_b64 s[8:9], s[2:3], s[6:7]
	s_andn2_b64 vcc, exec, s[8:9]
	s_cbranch_vccnz .LBB0_1169
	s_mov_b32 s77, 0
	s_lshl_b64 s[2:3], s[76:77], 9
	v_or_b32_e32 v2, s2, v0
	v_mov_b32_e32 v3, s3
	s_mov_b64 s[2:3], 0x400000
	v_cmp_gt_u64_e32 vcc, s[2:3], v[2:3]
	s_and_saveexec_b64 s[4:5], vcc
	s_cbranch_execz .LBB0_1168
	v_lshlrev_b32_e32 v4, 3, v0
	s_add_u32 s10, s74, 0x23510000
	s_mov_b32 s81, s77
	v_and_b32_e32 v4, 0x78, v4
	s_addc_u32 s11, s75, 0
	s_lshl_b64 s[12:13], s[80:81], 9
	v_mov_b32_e32 v7, 0
	s_mov_b64 s[14:15], 0
	s_mov_b64 s[16:17], 0x200000
	s_movk_i32 s2, 0xff
	v_lshlrev_b32_e32 v8, 1, v4
	s_mov_b64 s[18:19], 0x3fffff
	v_mov_b32_e32 v5, 0x68
	v_mov_b32_e32 v20, 0x60
	v_mov_b32_e32 v21, 0x2400
	v_mov_b32_e32 v22, 0x2000
	v_mov_b32_e32 v23, 0x5510000
	v_mov_b32_e32 v24, 0x3510000
	global_load_dwordx4 v[36:39], v7, s[0:1] offset:96
	s_waitcnt vmcnt(0)
	s_branch .LBB0_1164

.LBB0_1164:
	v_bfe_u32 v12, v2, 4, 5
	v_bfe_u32 v9, v2, 11, 8
	v_lshrrev_b32_e32 v11, 9, v2
	v_cmp_gt_u64_e32 vcc, s[16:17], v[2:3]
	v_cmp_ne_u32_e64 s[6:7], s2, v9
	v_lshlrev_b32_e32 v10, 7, v12
	s_and_saveexec_b64 s[20:21], s[6:7]
	s_xor_b64 s[6:7], exec, s[20:21]
	s_cbranch_execz .LBB0_1166
	v_cndmask_b32_e32 v18, v38, v36, vcc
	v_cndmask_b32_e32 v19, v39, v37, vcc
	v_lshlrev_b32_e32 v6, 2, v11
	v_lshlrev_b32_e32 v10, 4, v9
	v_and_b32_e32 v6, 0x3000, v6
	v_add3_u32 v6, v10, v12, v6
	v_mul_u32_u24_e32 v6, 0x1d00, v6
	v_lshlrev_b32_e32 v6, 1, v6
	v_lshlrev_b32_e32 v13, 8, v11
	v_lshl_add_u64 v[14:15], s[10:11], 0, v[6:7]
	v_cndmask_b32_e32 v6, v21, v22, vcc
	v_lshl_add_u64 v[14:15], v[14:15], 0, v[6:7]
	v_and_b32_e32 v6, 0x300, v13
	v_lshlrev_b32_e32 v10, 7, v12
	v_mov_b32_e32 v9, v7
	v_lshl_add_u64 v[14:15], v[14:15], 0, v[6:7]
	v_or_b32_e32 v6, v10, v4
	v_lshl_add_u64 v[14:15], v[14:15], 0, v[8:9]
	v_lshlrev_b32_e32 v6, 2, v6
	global_load_dwordx4 v[14:17], v[14:15], off
	v_lshl_add_u64 v[12:13], v[18:19], 0, v[6:7]
	global_load_dwordx4 v[26:29], v[12:13], off offset:16
	global_load_dwordx4 v[30:33], v[12:13], off
	s_waitcnt vmcnt(2)
	v_and_b32_e32 v19, 0xffff0000, v14
	v_lshlrev_b32_e32 v18, 16, v14
	v_and_b32_e32 v35, 0xffff0000, v15
	v_lshlrev_b32_e32 v34, 16, v15
	v_and_b32_e32 v15, 0xffff0000, v16
	v_lshlrev_b32_e32 v14, 16, v16
	v_and_b32_e32 v13, 0xffff0000, v17
	v_lshlrev_b32_e32 v12, 16, v17
	s_waitcnt vmcnt(1)
	v_pk_add_f32 v[12:13], v[28:29], v[12:13]
	v_pk_add_f32 v[14:15], v[26:27], v[14:15]
	s_waitcnt vmcnt(0)
	v_pk_add_f32 v[16:17], v[32:33], v[34:35]
	v_pk_add_f32 v[18:19], v[30:31], v[18:19]
